# SwiGLU epilogue (G1,G8) hand-rewritten: row scales prefetched one unit ahead, 8-wide interleaved chains, no pk_mul/mov shuffles; f32 math reassociated (g*up)*(rs^2/(1+e))
# speedup vs baseline: 1.0024x; 1.0024x over previous
; #define PG8_STAGE(bufoff, gbase, voff) do { _Pragma("unroll") for (int _i = 0; _i < 2; ++_i) \
;         __builtin_amdgcn_global_load_lds((const unsigned*)((const char*)(gbase) + (voff)[_i]), (PG8_LAS unsigned*)(lds + (bufoff) + ldsw + _i * 8192), 16, 0, 0); } while (0)
; #define PG8_BAR __builtin_amdgcn_s_barrier()
; __device__ __forceinline__ void row_scales_direct(const float* rs, int row0, float (&rsv)[2][4]) {
; #pragma unroll
;     for (int ai = 0; ai < 2; ++ai)
; #pragma unroll
;         for (int m = 0; m < 4; ++m) rsv[ai][m] = ((const __attribute__((address_space(1))) float*)rs)[row0 + ai * HALF + m * 16];
; }
; template <class Epi, class Sched, bool ALIGN_EPI = false, bool SP2 = false>
; __device__ __forceinline__ void gemm_phase(PG8_LAS unsigned char* lds, const Gemm g, const Sched& S, const Epi& E, int wave_id) {
;     ...
;     for (int i = 0; i < 2; ++i) { int R, C; stage_rc(tid * 16 + i * 8192, R, C); const int Rb = Epi::PERM ? ((R & ~31) + perm32(R & 31)) : R;
;         voffA[i] = (unsigned)(R * K + C) * 2u; voffB[i] = (unsigned)(Rb * K + C) * 2u; }
;     const size_t kstep = (size_t)(BK * 2);
;     const size_t hstep = (size_t)HALF * K * 2;
;     const size_t tstep = 2 * hstep;
;     const unsigned ldsw = (unsigned)wid * 1024u;
;     const int aoff = lds_byte(wr * 64 + fr, fq * 8), boff = lds_byte(wc * 32 + fr, fq * 8);
;     ...
;     Unit cur, nxt; int ui = 0;
;     if (!S.next(0, cur)) return;
;     f32x4 acc[2][2][4][2];
; #pragma unroll
;     for (int a = 0; a < 2; ++a)
; #pragma unroll
;         for (int b = 0; b < 2; ++b)
; #pragma unroll
;             for (int m = 0; m < 4; ++m)
; #pragma unroll
;                 for (int n = 0; n < 2; ++n) acc[a][b][m][n] = (f32x4){0.f, 0.f, 0.f, 0.f};
;     bf16x8 At[4][2], B0[2][2], B1[2][2];
;     const char* cA = (const char*)g.A + (size_t)cur.pm * tstep + PG8_KOFF(cur.pn); const char* cB = (const char*)g.Bt + (size_t)cur.pn * tstep + PG8_KOFF(cur.pn);
;     S.a_ready(cur);
;     if constexpr (SP2) {
;         PG8_STAGE(PG8_SB(0, 0), cB, voffB); PG8_STAGE(PG8_SB(0, 1), cB + hstep, voffB); PG8_STAGE(PG8_SA(0, 0), cA, voffA); PG8_STAGE(PG8_SA(0, 1), cA + hstep, voffA);
;         if (wr == 1) PG8_BAR;
;         PG8_WAIT_V(2); PG8_BAR;
;         PG8_STAGE(PG8_SB(1, 0), cB + kstep, voffB); PG8_STAGE(PG8_SA(1, 0), cA + kstep, voffA); PG8_STAGE(PG8_SB(1, 1), cB + hstep + kstep, voffB);
;         PG8_WAIT_V(6); PG8_BAR;
.LBB0_229:
	s_add_u32 s48, s42, 0x12b00000
	s_addc_u32 s49, s43, 0
	s_add_u32 s42, s42, 0x3f700000
	s_addc_u32 s43, s43, 0
	s_lshl_b32 s38, s41, 5
	s_and_b32 s41, s38, 0x60
	s_add_i32 m0, s70, 0x18000
	v_lshl_add_u64 v[6:7], v[6:7], 0, s[14:15]
	s_lshl_b32 s51, s40, 13
	s_lshl_b32 s52, s41, 7
	s_waitcnt vmcnt(2)
	s_barrier
	global_load_lds_dwordx4 v[6:7], off
	v_lshl_add_u64 v[4:5], v[4:5], 0, s[14:15]
	s_add_i32 m0, s70, 0x1a000
	s_add_i32 s74, s70, 0x8000
	s_add_i32 s75, s70, 0xa000
	global_load_lds_dwordx4 v[4:5], off
	v_lshl_add_u64 v[0:1], v[0:1], 0, s[14:15]
	s_mov_b32 m0, s74
	s_add_u32 s38, s62, 0x80080
	global_load_lds_dwordx4 v[0:1], off
	v_lshl_add_u64 v[0:1], v[2:3], 0, s[14:15]
	s_mov_b32 m0, s75
	s_addc_u32 s39, s63, 0
	global_load_lds_dwordx4 v[0:1], off
	s_add_i32 m0, s70, 0x1c000
	v_lshl_add_u64 v[0:1], s[38:39], 0, v[194:195]
	global_load_lds_dwordx4 v[0:1], off
	v_lshl_add_u64 v[0:1], s[38:39], 0, v[128:129]
	s_add_i32 m0, s70, 0x1e000
	s_cmpk_lt_u32 s50, 0x100
	global_load_lds_dwordx4 v[0:1], off
	v_lshrrev_b32_e32 v1, 1, v8
	v_and_b32_e32 v1, 24, v1
	v_and_b32_e32 v0, 15, v8
	v_lshlrev_b32_e32 v2, 1, v1
	v_lshl_or_b32 v141, s40, 6, v0
	v_lshl_or_b32 v0, v0, 6, v2
	v_lshlrev_b32_e32 v2, 2, v8
	v_and_b32_e32 v2, 32, v2
	v_bitop3_b32 v3, v0, s51, v2 bitop3:0xde
	v_bitop3_b32 v143, v0, s52, v2 bitop3:0xde
	v_lshlrev_b32_e32 v0, 15, v13
	v_and_b32_e32 v0, 0xffff0000, v0
	v_or_b32_e32 v145, s41, v1
	v_lshl_add_u32 v0, v12, 12, v0
	v_and_b32_e32 v1, 1, v13
	v_lshl_or_b32 v0, v1, 6, v0
	v_lshl_add_u32 v134, v14, 1, v0
	v_lshlrev_b32_e32 v0, 15, v9
	v_and_b32_e32 v0, 0xffff0000, v0
	s_waitcnt vmcnt(6)
	v_lshl_add_u32 v0, v10, 12, v0
	v_and_b32_e32 v1, 1, v9
	v_lshl_or_b32 v0, v1, 6, v0
	v_readlane_b32 s38, v254, 25
	s_cselect_b64 s[50:51], -1, 0
	v_mov_b32_e32 v135, v195
	v_lshl_add_u32 v136, v11, 1, v0
	v_mov_b32_e32 v137, v195
	s_mov_b32 s76, 0
	v_add_u32_e32 v147, 0, v3
	v_readlane_b32 s77, v253, 62
	s_mov_b32 s81, s38
	v_lshl_add_u32 v166, s81, 8, v141
	v_ashrrev_i32_e32 v167, 31, v166
	v_lshl_add_u64 v[168:169], v[166:167], 2, s[42:43]
	global_load_dword v234, v[168:169], off
	global_load_dword v235, v[168:169], off offset:64
	global_load_dword v236, v[168:169], off offset:128
	global_load_dword v237, v[168:169], off offset:192
	global_load_dword v238, v[168:169], off offset:512
	global_load_dword v239, v[168:169], off offset:576
	global_load_dword v240, v[168:169], off offset:640
	global_load_dword v241, v[168:169], off offset:704
	s_barrier
	v_readlane_b32 s39, v254, 26
	s_branch .LBB0_232

; __device__ __forceinline__ unsigned cvt_pk_bf16(float lo, float hi) { unsigned r; asm volatile("v_cvt_pk_bf16_f32 %0, %1, %2" : "=v"(r) : "v"(lo), "v"(hi)); return r; }
; __device__ __forceinline__ float fast_sigmoid(float x) { return __builtin_amdgcn_rcpf(1.f + __builtin_amdgcn_exp2f(-1.4426950408889634f * x)); }
;     __device__ __forceinline__ void operator()(const f32x4 (&acc)[2][2][4][2], const Unit& u, int wr, int wc, int fr, int fq) const {
;         const int row0 = u.pm * BM + wr * 64 + fr, col0 = u.pn * HALF + wc * 32 + 8 * fq;
;         float rsv[2][4]; row_scales_direct(ssq, row0, rsv);
; #pragma unroll
;         for (int ai = 0; ai < 2; ++ai)
; #pragma unroll
;             for (int m = 0; m < 4; ++m) { float o[8];
; #pragma unroll
;                 for (int n = 0; n < 2; ++n)
; #pragma unroll
;                     for (int j = 0; j < 4; ++j) { const float g = acc[ai][0][m][n][j] * rsv[ai][m], up = acc[ai][1][m][n][j] * rsv[ai][m]; o[n * 4 + j] = g * fast_sigmoid(g) * up; }
;                 u32x4 w; w.x = cvt_pk_bf16(o[0], o[1]); w.y = cvt_pk_bf16(o[2], o[3]); w.z = cvt_pk_bf16(o[4], o[5]); w.w = cvt_pk_bf16(o[6], o[7]);
;                 *(u32x4*)(H + (size_t)(row0 + ai * HALF + m * 16) * ldh + col0) = w; }
.LBB0_238:
	v_mov_b32_e32 v242, v234
	v_mov_b32_e32 v243, v235
	v_mov_b32_e32 v244, v236
	v_mov_b32_e32 v245, v237
	v_mov_b32_e32 v246, v238
	v_mov_b32_e32 v247, v239
	v_mov_b32_e32 v250, v240
	v_mov_b32_e32 v251, v241
	s_and_b64 s[38:39], s[40:41], exec
	s_cselect_b32 s38, s54, s81
	v_lshl_add_u32 v166, s38, 8, v141
	v_ashrrev_i32_e32 v167, 31, v166
	v_lshl_add_u64 v[168:169], v[166:167], 2, s[42:43]
	global_load_dword v234, v[168:169], off
	global_load_dword v235, v[168:169], off offset:64
	global_load_dword v236, v[168:169], off offset:128
	global_load_dword v237, v[168:169], off offset:192
	global_load_dword v238, v[168:169], off offset:512
	global_load_dword v239, v[168:169], off offset:576
	global_load_dword v240, v[168:169], off offset:640
	global_load_dword v241, v[168:169], off offset:704
	v_lshl_add_u32 v138, s81, 8, v141
	v_lshl_or_b32 v170, s77, 7, v145
	v_ashrrev_i32_e32 v171, 31, v170
	s_movk_i32 s53, 0x2c00
	v_mov_b64_e32 v[160:161], s[48:49]
	v_lshlrev_b64 v[162:163], 1, v[170:171]
	s_waitcnt vmcnt(8)
	v_mul_f32_e32 v156, 0xbfb8aa3b, v242
	v_mul_f32_e32 v158, v242, v242
	v_rcp_f32_e32 v157, v158
	v_mad_i64_i32 v[164:165], s[38:39], v138, s53, v[160:161]
	v_lshl_add_u64 v[164:165], v[164:165], 0, v[162:163]
	v_mul_f32_e32 v148, v124, v156
	v_mul_f32_e32 v149, v125, v156
	v_mul_f32_e32 v150, v126, v156
	v_mul_f32_e32 v151, v127, v156
	v_mul_f32_e32 v152, v116, v156
	v_mul_f32_e32 v153, v117, v156
	v_mul_f32_e32 v154, v118, v156
	v_mul_f32_e32 v155, v119, v156
	v_exp_f32_e32 v148, v148
	v_exp_f32_e32 v149, v149
	v_exp_f32_e32 v150, v150
	v_exp_f32_e32 v151, v151
	v_exp_f32_e32 v152, v152
	v_exp_f32_e32 v153, v153
	v_exp_f32_e32 v154, v154
	v_exp_f32_e32 v155, v155
	v_fma_f32 v148, v148, v157, v157
	v_fma_f32 v149, v149, v157, v157
	v_fma_f32 v150, v150, v157, v157
	v_fma_f32 v151, v151, v157, v157
	v_fma_f32 v152, v152, v157, v157
	v_fma_f32 v153, v153, v157, v157
	v_fma_f32 v154, v154, v157, v157
	v_fma_f32 v155, v155, v157, v157
	v_rcp_f32_e32 v148, v148
	v_rcp_f32_e32 v149, v149
	v_rcp_f32_e32 v150, v150
	v_rcp_f32_e32 v151, v151
	v_rcp_f32_e32 v152, v152
	v_rcp_f32_e32 v153, v153
	v_rcp_f32_e32 v154, v154
	v_rcp_f32_e32 v155, v155
	v_mul_f32_e32 v124, v124, v120
	v_mul_f32_e32 v125, v125, v121
	v_mul_f32_e32 v126, v126, v122
	v_mul_f32_e32 v127, v127, v123
	v_mul_f32_e32 v116, v116, v112
	v_mul_f32_e32 v117, v117, v113
	v_mul_f32_e32 v118, v118, v114
	v_mul_f32_e32 v119, v119, v115
	v_mul_f32_e32 v124, v124, v148
	v_mul_f32_e32 v125, v125, v149
	v_mul_f32_e32 v126, v126, v150
	v_mul_f32_e32 v127, v127, v151
	v_mul_f32_e32 v116, v116, v152
	v_mul_f32_e32 v117, v117, v153
	v_mul_f32_e32 v118, v118, v154
	v_mul_f32_e32 v119, v119, v155
	v_cvt_pk_bf16_f32 v120, v124, v125
	v_cvt_pk_bf16_f32 v121, v126, v127
	v_cvt_pk_bf16_f32 v122, v116, v117
	v_cvt_pk_bf16_f32 v123, v118, v119
	global_store_dwordx4 v[164:165], v[120:123], off
	v_mul_f32_e32 v156, 0xbfb8aa3b, v243
	v_mul_f32_e32 v158, v243, v243
	v_rcp_f32_e32 v157, v158
	v_add_u32_e32 v166, 0x10, v138
	v_mad_i64_i32 v[164:165], s[38:39], v166, s53, v[160:161]
	v_lshl_add_u64 v[164:165], v[164:165], 0, v[162:163]
	v_mul_f32_e32 v148, v108, v156
	v_mul_f32_e32 v149, v109, v156
	v_mul_f32_e32 v150, v110, v156
	v_mul_f32_e32 v151, v111, v156
	v_mul_f32_e32 v152, v100, v156
	v_mul_f32_e32 v153, v101, v156
	v_mul_f32_e32 v154, v102, v156
	v_mul_f32_e32 v155, v103, v156
	v_exp_f32_e32 v148, v148
	v_exp_f32_e32 v149, v149
	v_exp_f32_e32 v150, v150
	v_exp_f32_e32 v151, v151
	v_exp_f32_e32 v152, v152
	v_exp_f32_e32 v153, v153
	v_exp_f32_e32 v154, v154
	v_exp_f32_e32 v155, v155
	v_fma_f32 v148, v148, v157, v157
	v_fma_f32 v149, v149, v157, v157
	v_fma_f32 v150, v150, v157, v157
	v_fma_f32 v151, v151, v157, v157
	v_fma_f32 v152, v152, v157, v157
	v_fma_f32 v153, v153, v157, v157
	v_fma_f32 v154, v154, v157, v157
	v_fma_f32 v155, v155, v157, v157
	v_rcp_f32_e32 v148, v148
	v_rcp_f32_e32 v149, v149
	v_rcp_f32_e32 v150, v150
	v_rcp_f32_e32 v151, v151
	v_rcp_f32_e32 v152, v152
	v_rcp_f32_e32 v153, v153
	v_rcp_f32_e32 v154, v154
	v_rcp_f32_e32 v155, v155
	v_mul_f32_e32 v108, v108, v104
	v_mul_f32_e32 v109, v109, v105
	v_mul_f32_e32 v110, v110, v106
	v_mul_f32_e32 v111, v111, v107
	v_mul_f32_e32 v100, v100, v96
	v_mul_f32_e32 v101, v101, v97
	v_mul_f32_e32 v102, v102, v98
	v_mul_f32_e32 v103, v103, v99
	v_mul_f32_e32 v108, v108, v148
	v_mul_f32_e32 v109, v109, v149
	v_mul_f32_e32 v110, v110, v150
	v_mul_f32_e32 v111, v111, v151
	v_mul_f32_e32 v100, v100, v152
	v_mul_f32_e32 v101, v101, v153
	v_mul_f32_e32 v102, v102, v154
	v_mul_f32_e32 v103, v103, v155
	v_cvt_pk_bf16_f32 v104, v108, v109
	v_cvt_pk_bf16_f32 v105, v110, v111
	v_cvt_pk_bf16_f32 v106, v100, v101
	v_cvt_pk_bf16_f32 v107, v102, v103
	global_store_dwordx4 v[164:165], v[104:107], off
	v_mul_f32_e32 v156, 0xbfb8aa3b, v244
	v_mul_f32_e32 v158, v244, v244
	v_rcp_f32_e32 v157, v158
	v_add_u32_e32 v166, 0x20, v138
	v_mad_i64_i32 v[164:165], s[38:39], v166, s53, v[160:161]
	v_lshl_add_u64 v[164:165], v[164:165], 0, v[162:163]
	v_mul_f32_e32 v148, v92, v156
	v_mul_f32_e32 v149, v93, v156
	v_mul_f32_e32 v150, v94, v156
	v_mul_f32_e32 v151, v95, v156
	v_mul_f32_e32 v152, v84, v156
	v_mul_f32_e32 v153, v85, v156
	v_mul_f32_e32 v154, v86, v156
	v_mul_f32_e32 v155, v87, v156
	v_exp_f32_e32 v148, v148
	v_exp_f32_e32 v149, v149
	v_exp_f32_e32 v150, v150
	v_exp_f32_e32 v151, v151
	v_exp_f32_e32 v152, v152
	v_exp_f32_e32 v153, v153
	v_exp_f32_e32 v154, v154
	v_exp_f32_e32 v155, v155
	v_fma_f32 v148, v148, v157, v157
	v_fma_f32 v149, v149, v157, v157
	v_fma_f32 v150, v150, v157, v157
	v_fma_f32 v151, v151, v157, v157
	v_fma_f32 v152, v152, v157, v157
; __device__ __forceinline__ unsigned cvt_pk_bf16(float lo, float hi) { unsigned r; asm volatile("v_cvt_pk_bf16_f32 %0, %1, %2" : "=v"(r) : "v"(lo), "v"(hi)); return r; }
; __device__ __forceinline__ float fast_sigmoid(float x) { return __builtin_amdgcn_rcpf(1.f + __builtin_amdgcn_exp2f(-1.4426950408889634f * x)); }
;     __device__ __forceinline__ void operator()(const f32x4 (&acc)[2][2][4][2], const Unit& u, int wr, int wc, int fr, int fq) const {
;         const int row0 = u.pm * BM + wr * 64 + fr, col0 = u.pn * HALF + wc * 32 + 8 * fq;
;         float rsv[2][4]; row_scales_direct(ssq, row0, rsv);
; #pragma unroll
;         for (int ai = 0; ai < 2; ++ai)
; #pragma unroll
;             for (int m = 0; m < 4; ++m) { float o[8];
; #pragma unroll
;                 for (int n = 0; n < 2; ++n)
; #pragma unroll
;                     for (int j = 0; j < 4; ++j) { const float g = acc[ai][0][m][n][j] * rsv[ai][m], up = acc[ai][1][m][n][j] * rsv[ai][m]; o[n * 4 + j] = g * fast_sigmoid(g) * up; }
;                 u32x4 w; w.x = cvt_pk_bf16(o[0], o[1]); w.y = cvt_pk_bf16(o[2], o[3]); w.z = cvt_pk_bf16(o[4], o[5]); w.w = cvt_pk_bf16(o[6], o[7]);
;                 *(u32x4*)(H + (size_t)(row0 + ai * HALF + m * 16) * ldh + col0) = w; }
	v_fma_f32 v153, v153, v157, v157
	v_fma_f32 v154, v154, v157, v157
	v_fma_f32 v155, v155, v157, v157
	v_rcp_f32_e32 v148, v148
	v_rcp_f32_e32 v149, v149
	v_rcp_f32_e32 v150, v150
	v_rcp_f32_e32 v151, v151
	v_rcp_f32_e32 v152, v152
	v_rcp_f32_e32 v153, v153
	v_rcp_f32_e32 v154, v154
	v_rcp_f32_e32 v155, v155
	v_mul_f32_e32 v92, v92, v88
	v_mul_f32_e32 v93, v93, v89
	v_mul_f32_e32 v94, v94, v90
	v_mul_f32_e32 v95, v95, v91
	v_mul_f32_e32 v84, v84, v80
	v_mul_f32_e32 v85, v85, v81
	v_mul_f32_e32 v86, v86, v82
	v_mul_f32_e32 v87, v87, v83
	v_mul_f32_e32 v92, v92, v148
	v_mul_f32_e32 v93, v93, v149
	v_mul_f32_e32 v94, v94, v150
	v_mul_f32_e32 v95, v95, v151
	v_mul_f32_e32 v84, v84, v152
	v_mul_f32_e32 v85, v85, v153
	v_mul_f32_e32 v86, v86, v154
	v_mul_f32_e32 v87, v87, v155
	v_cvt_pk_bf16_f32 v88, v92, v93
	v_cvt_pk_bf16_f32 v89, v94, v95
	v_cvt_pk_bf16_f32 v90, v84, v85
	v_cvt_pk_bf16_f32 v91, v86, v87
	global_store_dwordx4 v[164:165], v[88:91], off
	v_mul_f32_e32 v156, 0xbfb8aa3b, v245
	v_mul_f32_e32 v158, v245, v245
	v_rcp_f32_e32 v157, v158
	v_add_u32_e32 v166, 0x30, v138
	v_mad_i64_i32 v[164:165], s[38:39], v166, s53, v[160:161]
	v_lshl_add_u64 v[164:165], v[164:165], 0, v[162:163]
	v_mul_f32_e32 v148, v76, v156
	v_mul_f32_e32 v149, v77, v156
	v_mul_f32_e32 v150, v78, v156
	v_mul_f32_e32 v151, v79, v156
	v_mul_f32_e32 v152, v68, v156
	v_mul_f32_e32 v153, v69, v156
	v_mul_f32_e32 v154, v70, v156
	v_mul_f32_e32 v155, v71, v156
	v_exp_f32_e32 v148, v148
	v_exp_f32_e32 v149, v149
	v_exp_f32_e32 v150, v150
	v_exp_f32_e32 v151, v151
	v_exp_f32_e32 v152, v152
	v_exp_f32_e32 v153, v153
	v_exp_f32_e32 v154, v154
	v_exp_f32_e32 v155, v155
	v_fma_f32 v148, v148, v157, v157
	v_fma_f32 v149, v149, v157, v157
	v_fma_f32 v150, v150, v157, v157
	v_fma_f32 v151, v151, v157, v157
	v_fma_f32 v152, v152, v157, v157
	v_fma_f32 v153, v153, v157, v157
	v_fma_f32 v154, v154, v157, v157
	v_fma_f32 v155, v155, v157, v157
	v_rcp_f32_e32 v148, v148
	v_rcp_f32_e32 v149, v149
	v_rcp_f32_e32 v150, v150
	v_rcp_f32_e32 v151, v151
	v_rcp_f32_e32 v152, v152
	v_rcp_f32_e32 v153, v153
	v_rcp_f32_e32 v154, v154
	v_rcp_f32_e32 v155, v155
	v_mul_f32_e32 v76, v76, v72
	v_mul_f32_e32 v77, v77, v73
	v_mul_f32_e32 v78, v78, v74
	v_mul_f32_e32 v79, v79, v75
	v_mul_f32_e32 v68, v68, v64
	v_mul_f32_e32 v69, v69, v65
	v_mul_f32_e32 v70, v70, v66
	v_mul_f32_e32 v71, v71, v67
	v_mul_f32_e32 v76, v76, v148
	v_mul_f32_e32 v77, v77, v149
	v_mul_f32_e32 v78, v78, v150
	v_mul_f32_e32 v79, v79, v151
	v_mul_f32_e32 v68, v68, v152
	v_mul_f32_e32 v69, v69, v153
	v_mul_f32_e32 v70, v70, v154
	v_mul_f32_e32 v71, v71, v155
	v_cvt_pk_bf16_f32 v72, v76, v77
	v_cvt_pk_bf16_f32 v73, v78, v79
	v_cvt_pk_bf16_f32 v74, v68, v69
	v_cvt_pk_bf16_f32 v75, v70, v71
	global_store_dwordx4 v[164:165], v[72:75], off
	v_mul_f32_e32 v156, 0xbfb8aa3b, v246
	v_mul_f32_e32 v158, v246, v246
	v_rcp_f32_e32 v157, v158
	v_add_u32_e32 v166, 0x80, v138
	v_mad_i64_i32 v[164:165], s[38:39], v166, s53, v[160:161]
	v_lshl_add_u64 v[164:165], v[164:165], 0, v[162:163]
	v_mul_f32_e32 v148, v60, v156
	v_mul_f32_e32 v149, v61, v156
	v_mul_f32_e32 v150, v62, v156
	v_mul_f32_e32 v151, v63, v156
	v_mul_f32_e32 v152, v52, v156
	v_mul_f32_e32 v153, v53, v156
	v_mul_f32_e32 v154, v54, v156
	v_mul_f32_e32 v155, v55, v156
	v_exp_f32_e32 v148, v148
	v_exp_f32_e32 v149, v149
	v_exp_f32_e32 v150, v150
	v_exp_f32_e32 v151, v151
	v_exp_f32_e32 v152, v152
	v_exp_f32_e32 v153, v153
	v_exp_f32_e32 v154, v154
	v_exp_f32_e32 v155, v155
	v_fma_f32 v148, v148, v157, v157
	v_fma_f32 v149, v149, v157, v157
	v_fma_f32 v150, v150, v157, v157
	v_fma_f32 v151, v151, v157, v157
	v_fma_f32 v152, v152, v157, v157
	v_fma_f32 v153, v153, v157, v157
	v_fma_f32 v154, v154, v157, v157
	v_fma_f32 v155, v155, v157, v157
	v_rcp_f32_e32 v148, v148
	v_rcp_f32_e32 v149, v149
	v_rcp_f32_e32 v150, v150
	v_rcp_f32_e32 v151, v151
	v_rcp_f32_e32 v152, v152
	v_rcp_f32_e32 v153, v153
	v_rcp_f32_e32 v154, v154
	v_rcp_f32_e32 v155, v155
	v_mul_f32_e32 v60, v60, v56
	v_mul_f32_e32 v61, v61, v57
	v_mul_f32_e32 v62, v62, v58
	v_mul_f32_e32 v63, v63, v59
	v_mul_f32_e32 v52, v52, v48
	v_mul_f32_e32 v53, v53, v49
	v_mul_f32_e32 v54, v54, v50
	v_mul_f32_e32 v55, v55, v51
	v_mul_f32_e32 v60, v60, v148
	v_mul_f32_e32 v61, v61, v149
	v_mul_f32_e32 v62, v62, v150
	v_mul_f32_e32 v63, v63, v151
	v_mul_f32_e32 v52, v52, v152
	v_mul_f32_e32 v53, v53, v153
	v_mul_f32_e32 v54, v54, v154
	v_mul_f32_e32 v55, v55, v155
	v_cvt_pk_bf16_f32 v56, v60, v61
	v_cvt_pk_bf16_f32 v57, v62, v63
	v_cvt_pk_bf16_f32 v58, v52, v53
	v_cvt_pk_bf16_f32 v59, v54, v55
	global_store_dwordx4 v[164:165], v[56:59], off
	v_mul_f32_e32 v156, 0xbfb8aa3b, v247
	v_mul_f32_e32 v158, v247, v247
	v_rcp_f32_e32 v157, v158
	v_add_u32_e32 v166, 0x90, v138
	v_mad_i64_i32 v[164:165], s[38:39], v166, s53, v[160:161]
	v_lshl_add_u64 v[164:165], v[164:165], 0, v[162:163]
	v_mul_f32_e32 v148, v44, v156
	v_mul_f32_e32 v149, v45, v156
	v_mul_f32_e32 v150, v46, v156
	v_mul_f32_e32 v151, v47, v156
	v_mul_f32_e32 v152, v36, v156
	v_mul_f32_e32 v153, v37, v156
	v_mul_f32_e32 v154, v38, v156
	v_mul_f32_e32 v155, v39, v156
	v_exp_f32_e32 v148, v148
; __device__ __forceinline__ unsigned cvt_pk_bf16(float lo, float hi) { unsigned r; asm volatile("v_cvt_pk_bf16_f32 %0, %1, %2" : "=v"(r) : "v"(lo), "v"(hi)); return r; }
; __device__ __forceinline__ float fast_sigmoid(float x) { return __builtin_amdgcn_rcpf(1.f + __builtin_amdgcn_exp2f(-1.4426950408889634f * x)); }
;     __device__ __forceinline__ void operator()(const f32x4 (&acc)[2][2][4][2], const Unit& u, int wr, int wc, int fr, int fq) const {
;         const int row0 = u.pm * BM + wr * 64 + fr, col0 = u.pn * HALF + wc * 32 + 8 * fq;
;         float rsv[2][4]; row_scales_direct(ssq, row0, rsv);
; #pragma unroll
;         for (int ai = 0; ai < 2; ++ai)
; #pragma unroll
;             for (int m = 0; m < 4; ++m) { float o[8];
; #pragma unroll
;                 for (int n = 0; n < 2; ++n)
; #pragma unroll
;                     for (int j = 0; j < 4; ++j) { const float g = acc[ai][0][m][n][j] * rsv[ai][m], up = acc[ai][1][m][n][j] * rsv[ai][m]; o[n * 4 + j] = g * fast_sigmoid(g) * up; }
;                 u32x4 w; w.x = cvt_pk_bf16(o[0], o[1]); w.y = cvt_pk_bf16(o[2], o[3]); w.z = cvt_pk_bf16(o[4], o[5]); w.w = cvt_pk_bf16(o[6], o[7]);
;                 *(u32x4*)(H + (size_t)(row0 + ai * HALF + m * 16) * ldh + col0) = w; }
; template <class Epi, class Sched, bool ALIGN_EPI = false, bool SP2 = false>
; __device__ __forceinline__ void gemm_phase(PG8_LAS unsigned char* lds, const Gemm g, const Sched& S, const Epi& E, int wave_id) {
;     ...
;         if (!has_next) break;
	v_exp_f32_e32 v149, v149
	v_exp_f32_e32 v150, v150
	v_exp_f32_e32 v151, v151
	v_exp_f32_e32 v152, v152
	v_exp_f32_e32 v153, v153
	v_exp_f32_e32 v154, v154
	v_exp_f32_e32 v155, v155
	v_fma_f32 v148, v148, v157, v157
	v_fma_f32 v149, v149, v157, v157
	v_fma_f32 v150, v150, v157, v157
	v_fma_f32 v151, v151, v157, v157
	v_fma_f32 v152, v152, v157, v157
	v_fma_f32 v153, v153, v157, v157
	v_fma_f32 v154, v154, v157, v157
	v_fma_f32 v155, v155, v157, v157
	v_rcp_f32_e32 v148, v148
	v_rcp_f32_e32 v149, v149
	v_rcp_f32_e32 v150, v150
	v_rcp_f32_e32 v151, v151
	v_rcp_f32_e32 v152, v152
	v_rcp_f32_e32 v153, v153
	v_rcp_f32_e32 v154, v154
	v_rcp_f32_e32 v155, v155
	v_mul_f32_e32 v44, v44, v40
	v_mul_f32_e32 v45, v45, v41
	v_mul_f32_e32 v46, v46, v42
	v_mul_f32_e32 v47, v47, v43
	v_mul_f32_e32 v36, v36, v32
	v_mul_f32_e32 v37, v37, v33
	v_mul_f32_e32 v38, v38, v34
	v_mul_f32_e32 v39, v39, v35
	v_mul_f32_e32 v44, v44, v148
	v_mul_f32_e32 v45, v45, v149
	v_mul_f32_e32 v46, v46, v150
	v_mul_f32_e32 v47, v47, v151
	v_mul_f32_e32 v36, v36, v152
	v_mul_f32_e32 v37, v37, v153
	v_mul_f32_e32 v38, v38, v154
	v_mul_f32_e32 v39, v39, v155
	v_cvt_pk_bf16_f32 v40, v44, v45
	v_cvt_pk_bf16_f32 v41, v46, v47
	v_cvt_pk_bf16_f32 v42, v36, v37
	v_cvt_pk_bf16_f32 v43, v38, v39
	global_store_dwordx4 v[164:165], v[40:43], off
	v_mul_f32_e32 v156, 0xbfb8aa3b, v250
	v_mul_f32_e32 v158, v250, v250
	v_rcp_f32_e32 v157, v158
	v_add_u32_e32 v166, 0xa0, v138
	v_mad_i64_i32 v[164:165], s[38:39], v166, s53, v[160:161]
	v_lshl_add_u64 v[164:165], v[164:165], 0, v[162:163]
	v_mul_f32_e32 v148, v28, v156
	v_mul_f32_e32 v149, v29, v156
	v_mul_f32_e32 v150, v30, v156
	v_mul_f32_e32 v151, v31, v156
	v_mul_f32_e32 v152, v20, v156
	v_mul_f32_e32 v153, v21, v156
	v_mul_f32_e32 v154, v22, v156
	v_mul_f32_e32 v155, v23, v156
	v_exp_f32_e32 v148, v148
	v_exp_f32_e32 v149, v149
	v_exp_f32_e32 v150, v150
	v_exp_f32_e32 v151, v151
	v_exp_f32_e32 v152, v152
	v_exp_f32_e32 v153, v153
	v_exp_f32_e32 v154, v154
	v_exp_f32_e32 v155, v155
	v_fma_f32 v148, v148, v157, v157
	v_fma_f32 v149, v149, v157, v157
	v_fma_f32 v150, v150, v157, v157
	v_fma_f32 v151, v151, v157, v157
	v_fma_f32 v152, v152, v157, v157
	v_fma_f32 v153, v153, v157, v157
	v_fma_f32 v154, v154, v157, v157
	v_fma_f32 v155, v155, v157, v157
	v_rcp_f32_e32 v148, v148
	v_rcp_f32_e32 v149, v149
	v_rcp_f32_e32 v150, v150
	v_rcp_f32_e32 v151, v151
	v_rcp_f32_e32 v152, v152
	v_rcp_f32_e32 v153, v153
	v_rcp_f32_e32 v154, v154
	v_rcp_f32_e32 v155, v155
	v_mul_f32_e32 v28, v28, v24
	v_mul_f32_e32 v29, v29, v25
	v_mul_f32_e32 v30, v30, v26
	v_mul_f32_e32 v31, v31, v27
	v_mul_f32_e32 v20, v20, v16
	v_mul_f32_e32 v21, v21, v17
	v_mul_f32_e32 v22, v22, v18
	v_mul_f32_e32 v23, v23, v19
	v_mul_f32_e32 v28, v28, v148
	v_mul_f32_e32 v29, v29, v149
	v_mul_f32_e32 v30, v30, v150
	v_mul_f32_e32 v31, v31, v151
	v_mul_f32_e32 v20, v20, v152
	v_mul_f32_e32 v21, v21, v153
	v_mul_f32_e32 v22, v22, v154
	v_mul_f32_e32 v23, v23, v155
	v_cvt_pk_bf16_f32 v24, v28, v29
	v_cvt_pk_bf16_f32 v25, v30, v31
	v_cvt_pk_bf16_f32 v26, v20, v21
	v_cvt_pk_bf16_f32 v27, v22, v23
	global_store_dwordx4 v[164:165], v[24:27], off
	v_mul_f32_e32 v156, 0xbfb8aa3b, v251
	v_mul_f32_e32 v158, v251, v251
	v_rcp_f32_e32 v157, v158
	v_add_u32_e32 v166, 0xb0, v138
	v_mad_i64_i32 v[164:165], s[38:39], v166, s53, v[160:161]
	v_lshl_add_u64 v[164:165], v[164:165], 0, v[162:163]
	v_mul_f32_e32 v148, v12, v156
	v_mul_f32_e32 v149, v13, v156
	v_mul_f32_e32 v150, v14, v156
	v_mul_f32_e32 v151, v15, v156
	v_mul_f32_e32 v152, v4, v156
	v_mul_f32_e32 v153, v5, v156
	v_mul_f32_e32 v154, v6, v156
	v_mul_f32_e32 v155, v7, v156
	v_exp_f32_e32 v148, v148
	v_exp_f32_e32 v149, v149
	v_exp_f32_e32 v150, v150
	v_exp_f32_e32 v151, v151
	v_exp_f32_e32 v152, v152
	v_exp_f32_e32 v153, v153
	v_exp_f32_e32 v154, v154
	v_exp_f32_e32 v155, v155
	v_fma_f32 v148, v148, v157, v157
	v_fma_f32 v149, v149, v157, v157
	v_fma_f32 v150, v150, v157, v157
	v_fma_f32 v151, v151, v157, v157
	v_fma_f32 v152, v152, v157, v157
	v_fma_f32 v153, v153, v157, v157
	v_fma_f32 v154, v154, v157, v157
	v_fma_f32 v155, v155, v157, v157
	v_rcp_f32_e32 v148, v148
	v_rcp_f32_e32 v149, v149
	v_rcp_f32_e32 v150, v150
	v_rcp_f32_e32 v151, v151
	v_rcp_f32_e32 v152, v152
	v_rcp_f32_e32 v153, v153
	v_rcp_f32_e32 v154, v154
	v_rcp_f32_e32 v155, v155
	v_mul_f32_e32 v12, v12, v8
	v_mul_f32_e32 v13, v13, v9
	v_mul_f32_e32 v14, v14, v10
	v_mul_f32_e32 v15, v15, v11
	v_mul_f32_e32 v4, v4, v0
	v_mul_f32_e32 v5, v5, v1
	v_mul_f32_e32 v6, v6, v2
	v_mul_f32_e32 v7, v7, v3
	v_mul_f32_e32 v12, v12, v148
	v_mul_f32_e32 v13, v13, v149
	v_mul_f32_e32 v14, v14, v150
	v_mul_f32_e32 v15, v15, v151
	v_mul_f32_e32 v4, v4, v152
	v_mul_f32_e32 v5, v5, v153
	v_mul_f32_e32 v6, v6, v154
	v_mul_f32_e32 v7, v7, v155
	v_cvt_pk_bf16_f32 v8, v12, v13
	v_cvt_pk_bf16_f32 v9, v14, v15
	v_cvt_pk_bf16_f32 v10, v4, v5
	v_cvt_pk_bf16_f32 v11, v6, v7
	global_store_dwordx4 v[164:165], v[8:11], off
	s_mov_b64 s[60:61], -1
	s_andn2_b64 vcc, exec, s[40:41]
	s_cbranch_vccnz .LBB0_231
	s_andn2_b64 vcc, exec, s[46:47]
	s_cbranch_vccnz .LBB0_230
	s_barrier
	s_branch .LBB0_230

; #define PG8_STAGE(bufoff, gbase, voff) do { _Pragma("unroll") for (int _i = 0; _i < 2; ++_i) \
;         __builtin_amdgcn_global_load_lds((const unsigned*)((const char*)(gbase) + (voff)[_i]), (PG8_LAS unsigned*)(lds + (bufoff) + ldsw + _i * 8192), 16, 0, 0); } while (0)
; #define PG8_BAR __builtin_amdgcn_s_barrier()
; __device__ __forceinline__ void row_scales_direct(const float* rs, int row0, float (&rsv)[2][4]) {
; #pragma unroll
;     for (int ai = 0; ai < 2; ++ai)
; #pragma unroll
;         for (int m = 0; m < 4; ++m) rsv[ai][m] = ((const __attribute__((address_space(1))) float*)rs)[row0 + ai * HALF + m * 16];
; }
; template <class Epi, class Sched, bool ALIGN_EPI = false, bool SP2 = false>
; __device__ __forceinline__ void gemm_phase(PG8_LAS unsigned char* lds, const Gemm g, const Sched& S, const Epi& E, int wave_id) {
;     ...
;     for (int i = 0; i < 2; ++i) { int R, C; stage_rc(tid * 16 + i * 8192, R, C); const int Rb = Epi::PERM ? ((R & ~31) + perm32(R & 31)) : R;
;         voffA[i] = (unsigned)(R * K + C) * 2u; voffB[i] = (unsigned)(Rb * K + C) * 2u; }
;     const size_t kstep = (size_t)(BK * 2);
;     const size_t hstep = (size_t)HALF * K * 2;
;     const size_t tstep = 2 * hstep;
;     const unsigned ldsw = (unsigned)wid * 1024u;
;     const int aoff = lds_byte(wr * 64 + fr, fq * 8), boff = lds_byte(wc * 32 + fr, fq * 8);
;     ...
;     Unit cur, nxt; int ui = 0;
;     if (!S.next(0, cur)) return;
;     f32x4 acc[2][2][4][2];
; #pragma unroll
;     for (int a = 0; a < 2; ++a)
; #pragma unroll
;         for (int b = 0; b < 2; ++b)
; #pragma unroll
;             for (int m = 0; m < 4; ++m)
; #pragma unroll
;                 for (int n = 0; n < 2; ++n) acc[a][b][m][n] = (f32x4){0.f, 0.f, 0.f, 0.f};
;     bf16x8 At[4][2], B0[2][2], B1[2][2];
;     const char* cA = (const char*)g.A + (size_t)cur.pm * tstep + PG8_KOFF(cur.pn); const char* cB = (const char*)g.Bt + (size_t)cur.pn * tstep + PG8_KOFF(cur.pn);
;     S.a_ready(cur);
;     if constexpr (SP2) {
;         PG8_STAGE(PG8_SB(0, 0), cB, voffB); PG8_STAGE(PG8_SB(0, 1), cB + hstep, voffB); PG8_STAGE(PG8_SA(0, 0), cA, voffA); PG8_STAGE(PG8_SA(0, 1), cA + hstep, voffA);
;         if (wr == 1) PG8_BAR;
;         PG8_WAIT_V(2); PG8_BAR;
;         PG8_STAGE(PG8_SB(1, 0), cB + kstep, voffB); PG8_STAGE(PG8_SA(1, 0), cA + kstep, voffA); PG8_STAGE(PG8_SB(1, 1), cB + hstep + kstep, voffB);
;         PG8_WAIT_V(6); PG8_BAR;
.LBB0_1696:
	s_add_u32 s44, s46, 0x12b00000
	s_addc_u32 s45, s47, 0
	s_add_u32 s46, s46, 0x3f700000
	s_addc_u32 s47, s47, 0
	s_lshl_b32 s40, s48, 5
	s_and_b32 s50, s40, 0x60
	s_add_i32 m0, s69, 0x18000
	v_lshl_add_u64 v[6:7], v[6:7], 0, s[14:15]
	s_lshl_b32 s49, s39, 13
	s_lshl_b32 s48, s50, 7
	s_waitcnt vmcnt(2)
	s_barrier
	global_load_lds_dwordx4 v[6:7], off
	v_lshl_add_u64 v[4:5], v[4:5], 0, s[14:15]
	s_add_i32 m0, s69, 0x1a000
	s_add_i32 s73, s69, 0x8000
	s_add_i32 s74, s69, 0xa000
	global_load_lds_dwordx4 v[4:5], off
	v_lshl_add_u64 v[0:1], v[0:1], 0, s[14:15]
	s_mov_b32 m0, s73
	s_add_u32 s40, s60, 0x80080
	global_load_lds_dwordx4 v[0:1], off
	v_lshl_add_u64 v[0:1], v[2:3], 0, s[14:15]
	s_mov_b32 m0, s74
	s_addc_u32 s41, s61, 0
	global_load_lds_dwordx4 v[0:1], off
	s_add_i32 m0, s69, 0x1c000
	v_lshl_add_u64 v[0:1], s[40:41], 0, v[194:195]
	global_load_lds_dwordx4 v[0:1], off
	v_lshl_add_u64 v[0:1], s[40:41], 0, v[128:129]
	s_add_i32 m0, s69, 0x1e000
	s_cmpk_lt_u32 s38, 0x100
	global_load_lds_dwordx4 v[0:1], off
	v_lshrrev_b32_e32 v1, 1, v8
	v_and_b32_e32 v1, 24, v1
	v_and_b32_e32 v0, 15, v8
	v_lshlrev_b32_e32 v2, 1, v1
	v_lshl_or_b32 v141, s39, 6, v0
	v_lshl_or_b32 v0, v0, 6, v2
	v_lshlrev_b32_e32 v2, 2, v8
	v_and_b32_e32 v2, 32, v2
	v_bitop3_b32 v3, v0, s49, v2 bitop3:0xde
	v_bitop3_b32 v143, v0, s48, v2 bitop3:0xde
	v_lshlrev_b32_e32 v0, 15, v13
	v_and_b32_e32 v0, 0xffff0000, v0
	v_or_b32_e32 v145, s50, v1
	v_lshl_add_u32 v0, v12, 12, v0
	v_and_b32_e32 v1, 1, v13
	v_lshl_or_b32 v0, v1, 6, v0
	v_lshl_add_u32 v134, v14, 1, v0
	v_lshlrev_b32_e32 v0, 15, v9
	v_and_b32_e32 v0, 0xffff0000, v0
	s_waitcnt vmcnt(6)
	v_lshl_add_u32 v0, v10, 12, v0
	v_and_b32_e32 v1, 1, v9
	v_lshl_or_b32 v0, v1, 6, v0
	v_readlane_b32 s38, v254, 25
	s_cselect_b64 s[48:49], -1, 0
	v_mov_b32_e32 v135, v195
	v_lshl_add_u32 v136, v11, 1, v0
	v_mov_b32_e32 v137, v195
	s_mov_b32 s75, 0
	v_add_u32_e32 v147, 0, v3
	v_readlane_b32 s76, v253, 62
	s_mov_b32 s77, s38
	v_lshl_add_u32 v166, s77, 8, v141
	v_ashrrev_i32_e32 v167, 31, v166
	v_lshl_add_u64 v[168:169], v[166:167], 2, s[46:47]
	global_load_dword v234, v[168:169], off
	global_load_dword v235, v[168:169], off offset:64
	global_load_dword v236, v[168:169], off offset:128
	global_load_dword v237, v[168:169], off offset:192
	global_load_dword v238, v[168:169], off offset:512
	global_load_dword v239, v[168:169], off offset:576
	global_load_dword v240, v[168:169], off offset:640
	global_load_dword v241, v[168:169], off offset:704
	s_barrier
	v_readlane_b32 s39, v254, 26
	s_branch .LBB0_1699

; __device__ __forceinline__ unsigned cvt_pk_bf16(float lo, float hi) { unsigned r; asm volatile("v_cvt_pk_bf16_f32 %0, %1, %2" : "=v"(r) : "v"(lo), "v"(hi)); return r; }
; __device__ __forceinline__ float fast_sigmoid(float x) { return __builtin_amdgcn_rcpf(1.f + __builtin_amdgcn_exp2f(-1.4426950408889634f * x)); }
;     __device__ __forceinline__ void operator()(const f32x4 (&acc)[2][2][4][2], const Unit& u, int wr, int wc, int fr, int fq) const {
;         const int row0 = u.pm * BM + wr * 64 + fr, col0 = u.pn * HALF + wc * 32 + 8 * fq;
;         float rsv[2][4]; row_scales_direct(ssq, row0, rsv);
; #pragma unroll
;         for (int ai = 0; ai < 2; ++ai)
; #pragma unroll
;             for (int m = 0; m < 4; ++m) { float o[8];
; #pragma unroll
;                 for (int n = 0; n < 2; ++n)
; #pragma unroll
;                     for (int j = 0; j < 4; ++j) { const float g = acc[ai][0][m][n][j] * rsv[ai][m], up = acc[ai][1][m][n][j] * rsv[ai][m]; o[n * 4 + j] = g * fast_sigmoid(g) * up; }
;                 u32x4 w; w.x = cvt_pk_bf16(o[0], o[1]); w.y = cvt_pk_bf16(o[2], o[3]); w.z = cvt_pk_bf16(o[4], o[5]); w.w = cvt_pk_bf16(o[6], o[7]);
;                 *(u32x4*)(H + (size_t)(row0 + ai * HALF + m * 16) * ldh + col0) = w; }
.LBB0_1705:
	v_mov_b32_e32 v242, v234
	v_mov_b32_e32 v243, v235
	v_mov_b32_e32 v244, v236
	v_mov_b32_e32 v245, v237
	v_mov_b32_e32 v246, v238
	v_mov_b32_e32 v247, v239
	v_mov_b32_e32 v250, v240
	v_mov_b32_e32 v251, v241
	s_and_b64 s[40:41], s[38:39], exec
	s_cselect_b32 s40, s52, s77
	v_lshl_add_u32 v166, s40, 8, v141
	v_ashrrev_i32_e32 v167, 31, v166
	v_lshl_add_u64 v[168:169], v[166:167], 2, s[46:47]
	global_load_dword v234, v[168:169], off
	global_load_dword v235, v[168:169], off offset:64
	global_load_dword v236, v[168:169], off offset:128
	global_load_dword v237, v[168:169], off offset:192
	global_load_dword v238, v[168:169], off offset:512
	global_load_dword v239, v[168:169], off offset:576
	global_load_dword v240, v[168:169], off offset:640
	global_load_dword v241, v[168:169], off offset:704
	v_lshl_add_u32 v138, s77, 8, v141
	v_lshl_or_b32 v170, s76, 7, v145
	v_ashrrev_i32_e32 v171, 31, v170
	s_movk_i32 s51, 0x2c00
	v_mov_b64_e32 v[160:161], s[44:45]
	v_lshlrev_b64 v[162:163], 1, v[170:171]
	s_waitcnt vmcnt(8)
	v_mul_f32_e32 v156, 0xbfb8aa3b, v242
	v_mul_f32_e32 v158, v242, v242
	v_rcp_f32_e32 v157, v158
	v_mad_i64_i32 v[164:165], s[40:41], v138, s51, v[160:161]
	v_lshl_add_u64 v[164:165], v[164:165], 0, v[162:163]
	v_mul_f32_e32 v148, v124, v156
	v_mul_f32_e32 v149, v125, v156
	v_mul_f32_e32 v150, v126, v156
	v_mul_f32_e32 v151, v127, v156
	v_mul_f32_e32 v152, v116, v156
	v_mul_f32_e32 v153, v117, v156
	v_mul_f32_e32 v154, v118, v156
	v_mul_f32_e32 v155, v119, v156
	v_exp_f32_e32 v148, v148
	v_exp_f32_e32 v149, v149
	v_exp_f32_e32 v150, v150
	v_exp_f32_e32 v151, v151
	v_exp_f32_e32 v152, v152
	v_exp_f32_e32 v153, v153
	v_exp_f32_e32 v154, v154
	v_exp_f32_e32 v155, v155
	v_fma_f32 v148, v148, v157, v157
	v_fma_f32 v149, v149, v157, v157
	v_fma_f32 v150, v150, v157, v157
	v_fma_f32 v151, v151, v157, v157
	v_fma_f32 v152, v152, v157, v157
	v_fma_f32 v153, v153, v157, v157
	v_fma_f32 v154, v154, v157, v157
	v_fma_f32 v155, v155, v157, v157
	v_rcp_f32_e32 v148, v148
	v_rcp_f32_e32 v149, v149
	v_rcp_f32_e32 v150, v150
	v_rcp_f32_e32 v151, v151
	v_rcp_f32_e32 v152, v152
	v_rcp_f32_e32 v153, v153
	v_rcp_f32_e32 v154, v154
	v_rcp_f32_e32 v155, v155
	v_mul_f32_e32 v124, v124, v120
	v_mul_f32_e32 v125, v125, v121
	v_mul_f32_e32 v126, v126, v122
	v_mul_f32_e32 v127, v127, v123
	v_mul_f32_e32 v116, v116, v112
	v_mul_f32_e32 v117, v117, v113
	v_mul_f32_e32 v118, v118, v114
	v_mul_f32_e32 v119, v119, v115
	v_mul_f32_e32 v124, v124, v148
	v_mul_f32_e32 v125, v125, v149
	v_mul_f32_e32 v126, v126, v150
	v_mul_f32_e32 v127, v127, v151
	v_mul_f32_e32 v116, v116, v152
	v_mul_f32_e32 v117, v117, v153
	v_mul_f32_e32 v118, v118, v154
	v_mul_f32_e32 v119, v119, v155
	v_cvt_pk_bf16_f32 v120, v124, v125
	v_cvt_pk_bf16_f32 v121, v126, v127
	v_cvt_pk_bf16_f32 v122, v116, v117
	v_cvt_pk_bf16_f32 v123, v118, v119
	global_store_dwordx4 v[164:165], v[120:123], off
	v_mul_f32_e32 v156, 0xbfb8aa3b, v243
	v_mul_f32_e32 v158, v243, v243
	v_rcp_f32_e32 v157, v158
	v_add_u32_e32 v166, 0x10, v138
	v_mad_i64_i32 v[164:165], s[40:41], v166, s51, v[160:161]
	v_lshl_add_u64 v[164:165], v[164:165], 0, v[162:163]
	v_mul_f32_e32 v148, v108, v156
	v_mul_f32_e32 v149, v109, v156
	v_mul_f32_e32 v150, v110, v156
	v_mul_f32_e32 v151, v111, v156
	v_mul_f32_e32 v152, v100, v156
	v_mul_f32_e32 v153, v101, v156
	v_mul_f32_e32 v154, v102, v156
	v_mul_f32_e32 v155, v103, v156
	v_exp_f32_e32 v148, v148
	v_exp_f32_e32 v149, v149
	v_exp_f32_e32 v150, v150
	v_exp_f32_e32 v151, v151
	v_exp_f32_e32 v152, v152
	v_exp_f32_e32 v153, v153
	v_exp_f32_e32 v154, v154
	v_exp_f32_e32 v155, v155
	v_fma_f32 v148, v148, v157, v157
	v_fma_f32 v149, v149, v157, v157
	v_fma_f32 v150, v150, v157, v157
	v_fma_f32 v151, v151, v157, v157
	v_fma_f32 v152, v152, v157, v157
	v_fma_f32 v153, v153, v157, v157
	v_fma_f32 v154, v154, v157, v157
	v_fma_f32 v155, v155, v157, v157
	v_rcp_f32_e32 v148, v148
	v_rcp_f32_e32 v149, v149
	v_rcp_f32_e32 v150, v150
	v_rcp_f32_e32 v151, v151
	v_rcp_f32_e32 v152, v152
	v_rcp_f32_e32 v153, v153
	v_rcp_f32_e32 v154, v154
	v_rcp_f32_e32 v155, v155
	v_mul_f32_e32 v108, v108, v104
	v_mul_f32_e32 v109, v109, v105
	v_mul_f32_e32 v110, v110, v106
	v_mul_f32_e32 v111, v111, v107
	v_mul_f32_e32 v100, v100, v96
	v_mul_f32_e32 v101, v101, v97
	v_mul_f32_e32 v102, v102, v98
	v_mul_f32_e32 v103, v103, v99
	v_mul_f32_e32 v108, v108, v148
	v_mul_f32_e32 v109, v109, v149
	v_mul_f32_e32 v110, v110, v150
	v_mul_f32_e32 v111, v111, v151
	v_mul_f32_e32 v100, v100, v152
	v_mul_f32_e32 v101, v101, v153
	v_mul_f32_e32 v102, v102, v154
	v_mul_f32_e32 v103, v103, v155
	v_cvt_pk_bf16_f32 v104, v108, v109
	v_cvt_pk_bf16_f32 v105, v110, v111
	v_cvt_pk_bf16_f32 v106, v100, v101
	v_cvt_pk_bf16_f32 v107, v102, v103
	global_store_dwordx4 v[164:165], v[104:107], off
	v_mul_f32_e32 v156, 0xbfb8aa3b, v244
	v_mul_f32_e32 v158, v244, v244
	v_rcp_f32_e32 v157, v158
	v_add_u32_e32 v166, 0x20, v138
	v_mad_i64_i32 v[164:165], s[40:41], v166, s51, v[160:161]
	v_lshl_add_u64 v[164:165], v[164:165], 0, v[162:163]
	v_mul_f32_e32 v148, v92, v156
	v_mul_f32_e32 v149, v93, v156
	v_mul_f32_e32 v150, v94, v156
	v_mul_f32_e32 v151, v95, v156
	v_mul_f32_e32 v152, v84, v156
	v_mul_f32_e32 v153, v85, v156
	v_mul_f32_e32 v154, v86, v156
	v_mul_f32_e32 v155, v87, v156
	v_exp_f32_e32 v148, v148
	v_exp_f32_e32 v149, v149
	v_exp_f32_e32 v150, v150
	v_exp_f32_e32 v151, v151
	v_exp_f32_e32 v152, v152
	v_exp_f32_e32 v153, v153
	v_exp_f32_e32 v154, v154
	v_exp_f32_e32 v155, v155
	v_fma_f32 v148, v148, v157, v157
	v_fma_f32 v149, v149, v157, v157
	v_fma_f32 v150, v150, v157, v157
	v_fma_f32 v151, v151, v157, v157
	v_fma_f32 v152, v152, v157, v157
; __device__ __forceinline__ unsigned cvt_pk_bf16(float lo, float hi) { unsigned r; asm volatile("v_cvt_pk_bf16_f32 %0, %1, %2" : "=v"(r) : "v"(lo), "v"(hi)); return r; }
; __device__ __forceinline__ float fast_sigmoid(float x) { return __builtin_amdgcn_rcpf(1.f + __builtin_amdgcn_exp2f(-1.4426950408889634f * x)); }
;     __device__ __forceinline__ void operator()(const f32x4 (&acc)[2][2][4][2], const Unit& u, int wr, int wc, int fr, int fq) const {
;         const int row0 = u.pm * BM + wr * 64 + fr, col0 = u.pn * HALF + wc * 32 + 8 * fq;
;         float rsv[2][4]; row_scales_direct(ssq, row0, rsv);
; #pragma unroll
;         for (int ai = 0; ai < 2; ++ai)
; #pragma unroll
;             for (int m = 0; m < 4; ++m) { float o[8];
; #pragma unroll
;                 for (int n = 0; n < 2; ++n)
; #pragma unroll
;                     for (int j = 0; j < 4; ++j) { const float g = acc[ai][0][m][n][j] * rsv[ai][m], up = acc[ai][1][m][n][j] * rsv[ai][m]; o[n * 4 + j] = g * fast_sigmoid(g) * up; }
;                 u32x4 w; w.x = cvt_pk_bf16(o[0], o[1]); w.y = cvt_pk_bf16(o[2], o[3]); w.z = cvt_pk_bf16(o[4], o[5]); w.w = cvt_pk_bf16(o[6], o[7]);
;                 *(u32x4*)(H + (size_t)(row0 + ai * HALF + m * 16) * ldh + col0) = w; }
	v_fma_f32 v153, v153, v157, v157
	v_fma_f32 v154, v154, v157, v157
	v_fma_f32 v155, v155, v157, v157
	v_rcp_f32_e32 v148, v148
	v_rcp_f32_e32 v149, v149
	v_rcp_f32_e32 v150, v150
	v_rcp_f32_e32 v151, v151
	v_rcp_f32_e32 v152, v152
	v_rcp_f32_e32 v153, v153
	v_rcp_f32_e32 v154, v154
	v_rcp_f32_e32 v155, v155
	v_mul_f32_e32 v92, v92, v88
	v_mul_f32_e32 v93, v93, v89
	v_mul_f32_e32 v94, v94, v90
	v_mul_f32_e32 v95, v95, v91
	v_mul_f32_e32 v84, v84, v80
	v_mul_f32_e32 v85, v85, v81
	v_mul_f32_e32 v86, v86, v82
	v_mul_f32_e32 v87, v87, v83
	v_mul_f32_e32 v92, v92, v148
	v_mul_f32_e32 v93, v93, v149
	v_mul_f32_e32 v94, v94, v150
	v_mul_f32_e32 v95, v95, v151
	v_mul_f32_e32 v84, v84, v152
	v_mul_f32_e32 v85, v85, v153
	v_mul_f32_e32 v86, v86, v154
	v_mul_f32_e32 v87, v87, v155
	v_cvt_pk_bf16_f32 v88, v92, v93
	v_cvt_pk_bf16_f32 v89, v94, v95
	v_cvt_pk_bf16_f32 v90, v84, v85
	v_cvt_pk_bf16_f32 v91, v86, v87
	global_store_dwordx4 v[164:165], v[88:91], off
	v_mul_f32_e32 v156, 0xbfb8aa3b, v245
	v_mul_f32_e32 v158, v245, v245
	v_rcp_f32_e32 v157, v158
	v_add_u32_e32 v166, 0x30, v138
	v_mad_i64_i32 v[164:165], s[40:41], v166, s51, v[160:161]
	v_lshl_add_u64 v[164:165], v[164:165], 0, v[162:163]
	v_mul_f32_e32 v148, v76, v156
	v_mul_f32_e32 v149, v77, v156
	v_mul_f32_e32 v150, v78, v156
	v_mul_f32_e32 v151, v79, v156
	v_mul_f32_e32 v152, v68, v156
	v_mul_f32_e32 v153, v69, v156
	v_mul_f32_e32 v154, v70, v156
	v_mul_f32_e32 v155, v71, v156
	v_exp_f32_e32 v148, v148
	v_exp_f32_e32 v149, v149
	v_exp_f32_e32 v150, v150
	v_exp_f32_e32 v151, v151
	v_exp_f32_e32 v152, v152
	v_exp_f32_e32 v153, v153
	v_exp_f32_e32 v154, v154
	v_exp_f32_e32 v155, v155
	v_fma_f32 v148, v148, v157, v157
	v_fma_f32 v149, v149, v157, v157
	v_fma_f32 v150, v150, v157, v157
	v_fma_f32 v151, v151, v157, v157
	v_fma_f32 v152, v152, v157, v157
	v_fma_f32 v153, v153, v157, v157
	v_fma_f32 v154, v154, v157, v157
	v_fma_f32 v155, v155, v157, v157
	v_rcp_f32_e32 v148, v148
	v_rcp_f32_e32 v149, v149
	v_rcp_f32_e32 v150, v150
	v_rcp_f32_e32 v151, v151
	v_rcp_f32_e32 v152, v152
	v_rcp_f32_e32 v153, v153
	v_rcp_f32_e32 v154, v154
	v_rcp_f32_e32 v155, v155
	v_mul_f32_e32 v76, v76, v72
	v_mul_f32_e32 v77, v77, v73
	v_mul_f32_e32 v78, v78, v74
	v_mul_f32_e32 v79, v79, v75
	v_mul_f32_e32 v68, v68, v64
	v_mul_f32_e32 v69, v69, v65
	v_mul_f32_e32 v70, v70, v66
	v_mul_f32_e32 v71, v71, v67
	v_mul_f32_e32 v76, v76, v148
	v_mul_f32_e32 v77, v77, v149
	v_mul_f32_e32 v78, v78, v150
	v_mul_f32_e32 v79, v79, v151
	v_mul_f32_e32 v68, v68, v152
	v_mul_f32_e32 v69, v69, v153
	v_mul_f32_e32 v70, v70, v154
	v_mul_f32_e32 v71, v71, v155
	v_cvt_pk_bf16_f32 v72, v76, v77
	v_cvt_pk_bf16_f32 v73, v78, v79
	v_cvt_pk_bf16_f32 v74, v68, v69
	v_cvt_pk_bf16_f32 v75, v70, v71
	global_store_dwordx4 v[164:165], v[72:75], off
	v_mul_f32_e32 v156, 0xbfb8aa3b, v246
	v_mul_f32_e32 v158, v246, v246
	v_rcp_f32_e32 v157, v158
	v_add_u32_e32 v166, 0x80, v138
	v_mad_i64_i32 v[164:165], s[40:41], v166, s51, v[160:161]
	v_lshl_add_u64 v[164:165], v[164:165], 0, v[162:163]
	v_mul_f32_e32 v148, v60, v156
	v_mul_f32_e32 v149, v61, v156
	v_mul_f32_e32 v150, v62, v156
	v_mul_f32_e32 v151, v63, v156
	v_mul_f32_e32 v152, v52, v156
	v_mul_f32_e32 v153, v53, v156
	v_mul_f32_e32 v154, v54, v156
	v_mul_f32_e32 v155, v55, v156
	v_exp_f32_e32 v148, v148
	v_exp_f32_e32 v149, v149
	v_exp_f32_e32 v150, v150
	v_exp_f32_e32 v151, v151
	v_exp_f32_e32 v152, v152
	v_exp_f32_e32 v153, v153
	v_exp_f32_e32 v154, v154
	v_exp_f32_e32 v155, v155
	v_fma_f32 v148, v148, v157, v157
	v_fma_f32 v149, v149, v157, v157
	v_fma_f32 v150, v150, v157, v157
	v_fma_f32 v151, v151, v157, v157
	v_fma_f32 v152, v152, v157, v157
	v_fma_f32 v153, v153, v157, v157
	v_fma_f32 v154, v154, v157, v157
	v_fma_f32 v155, v155, v157, v157
	v_rcp_f32_e32 v148, v148
	v_rcp_f32_e32 v149, v149
	v_rcp_f32_e32 v150, v150
	v_rcp_f32_e32 v151, v151
	v_rcp_f32_e32 v152, v152
	v_rcp_f32_e32 v153, v153
	v_rcp_f32_e32 v154, v154
	v_rcp_f32_e32 v155, v155
	v_mul_f32_e32 v60, v60, v56
	v_mul_f32_e32 v61, v61, v57
	v_mul_f32_e32 v62, v62, v58
	v_mul_f32_e32 v63, v63, v59
	v_mul_f32_e32 v52, v52, v48
	v_mul_f32_e32 v53, v53, v49
	v_mul_f32_e32 v54, v54, v50
	v_mul_f32_e32 v55, v55, v51
	v_mul_f32_e32 v60, v60, v148
	v_mul_f32_e32 v61, v61, v149
	v_mul_f32_e32 v62, v62, v150
	v_mul_f32_e32 v63, v63, v151
	v_mul_f32_e32 v52, v52, v152
	v_mul_f32_e32 v53, v53, v153
	v_mul_f32_e32 v54, v54, v154
	v_mul_f32_e32 v55, v55, v155
	v_cvt_pk_bf16_f32 v56, v60, v61
	v_cvt_pk_bf16_f32 v57, v62, v63
	v_cvt_pk_bf16_f32 v58, v52, v53
	v_cvt_pk_bf16_f32 v59, v54, v55
	global_store_dwordx4 v[164:165], v[56:59], off
	v_mul_f32_e32 v156, 0xbfb8aa3b, v247
	v_mul_f32_e32 v158, v247, v247
	v_rcp_f32_e32 v157, v158
	v_add_u32_e32 v166, 0x90, v138
	v_mad_i64_i32 v[164:165], s[40:41], v166, s51, v[160:161]
	v_lshl_add_u64 v[164:165], v[164:165], 0, v[162:163]
	v_mul_f32_e32 v148, v44, v156
	v_mul_f32_e32 v149, v45, v156
	v_mul_f32_e32 v150, v46, v156
	v_mul_f32_e32 v151, v47, v156
	v_mul_f32_e32 v152, v36, v156
	v_mul_f32_e32 v153, v37, v156
	v_mul_f32_e32 v154, v38, v156
	v_mul_f32_e32 v155, v39, v156
	v_exp_f32_e32 v148, v148
; __device__ __forceinline__ unsigned cvt_pk_bf16(float lo, float hi) { unsigned r; asm volatile("v_cvt_pk_bf16_f32 %0, %1, %2" : "=v"(r) : "v"(lo), "v"(hi)); return r; }
; __device__ __forceinline__ float fast_sigmoid(float x) { return __builtin_amdgcn_rcpf(1.f + __builtin_amdgcn_exp2f(-1.4426950408889634f * x)); }
;     __device__ __forceinline__ void operator()(const f32x4 (&acc)[2][2][4][2], const Unit& u, int wr, int wc, int fr, int fq) const {
;         const int row0 = u.pm * BM + wr * 64 + fr, col0 = u.pn * HALF + wc * 32 + 8 * fq;
;         float rsv[2][4]; row_scales_direct(ssq, row0, rsv);
; #pragma unroll
;         for (int ai = 0; ai < 2; ++ai)
; #pragma unroll
;             for (int m = 0; m < 4; ++m) { float o[8];
; #pragma unroll
;                 for (int n = 0; n < 2; ++n)
; #pragma unroll
;                     for (int j = 0; j < 4; ++j) { const float g = acc[ai][0][m][n][j] * rsv[ai][m], up = acc[ai][1][m][n][j] * rsv[ai][m]; o[n * 4 + j] = g * fast_sigmoid(g) * up; }
;                 u32x4 w; w.x = cvt_pk_bf16(o[0], o[1]); w.y = cvt_pk_bf16(o[2], o[3]); w.z = cvt_pk_bf16(o[4], o[5]); w.w = cvt_pk_bf16(o[6], o[7]);
;                 *(u32x4*)(H + (size_t)(row0 + ai * HALF + m * 16) * ldh + col0) = w; }
; template <class Epi, class Sched, bool ALIGN_EPI = false, bool SP2 = false>
; __device__ __forceinline__ void gemm_phase(PG8_LAS unsigned char* lds, const Gemm g, const Sched& S, const Epi& E, int wave_id) {
;     ...
;         if (!has_next) break;
	v_exp_f32_e32 v149, v149
	v_exp_f32_e32 v150, v150
	v_exp_f32_e32 v151, v151
	v_exp_f32_e32 v152, v152
	v_exp_f32_e32 v153, v153
	v_exp_f32_e32 v154, v154
	v_exp_f32_e32 v155, v155
	v_fma_f32 v148, v148, v157, v157
	v_fma_f32 v149, v149, v157, v157
	v_fma_f32 v150, v150, v157, v157
	v_fma_f32 v151, v151, v157, v157
	v_fma_f32 v152, v152, v157, v157
	v_fma_f32 v153, v153, v157, v157
	v_fma_f32 v154, v154, v157, v157
	v_fma_f32 v155, v155, v157, v157
	v_rcp_f32_e32 v148, v148
	v_rcp_f32_e32 v149, v149
	v_rcp_f32_e32 v150, v150
	v_rcp_f32_e32 v151, v151
	v_rcp_f32_e32 v152, v152
	v_rcp_f32_e32 v153, v153
	v_rcp_f32_e32 v154, v154
	v_rcp_f32_e32 v155, v155
	v_mul_f32_e32 v44, v44, v40
	v_mul_f32_e32 v45, v45, v41
	v_mul_f32_e32 v46, v46, v42
	v_mul_f32_e32 v47, v47, v43
	v_mul_f32_e32 v36, v36, v32
	v_mul_f32_e32 v37, v37, v33
	v_mul_f32_e32 v38, v38, v34
	v_mul_f32_e32 v39, v39, v35
	v_mul_f32_e32 v44, v44, v148
	v_mul_f32_e32 v45, v45, v149
	v_mul_f32_e32 v46, v46, v150
	v_mul_f32_e32 v47, v47, v151
	v_mul_f32_e32 v36, v36, v152
	v_mul_f32_e32 v37, v37, v153
	v_mul_f32_e32 v38, v38, v154
	v_mul_f32_e32 v39, v39, v155
	v_cvt_pk_bf16_f32 v40, v44, v45
	v_cvt_pk_bf16_f32 v41, v46, v47
	v_cvt_pk_bf16_f32 v42, v36, v37
	v_cvt_pk_bf16_f32 v43, v38, v39
	global_store_dwordx4 v[164:165], v[40:43], off
	v_mul_f32_e32 v156, 0xbfb8aa3b, v250
	v_mul_f32_e32 v158, v250, v250
	v_rcp_f32_e32 v157, v158
	v_add_u32_e32 v166, 0xa0, v138
	v_mad_i64_i32 v[164:165], s[40:41], v166, s51, v[160:161]
	v_lshl_add_u64 v[164:165], v[164:165], 0, v[162:163]
	v_mul_f32_e32 v148, v28, v156
	v_mul_f32_e32 v149, v29, v156
	v_mul_f32_e32 v150, v30, v156
	v_mul_f32_e32 v151, v31, v156
	v_mul_f32_e32 v152, v20, v156
	v_mul_f32_e32 v153, v21, v156
	v_mul_f32_e32 v154, v22, v156
	v_mul_f32_e32 v155, v23, v156
	v_exp_f32_e32 v148, v148
	v_exp_f32_e32 v149, v149
	v_exp_f32_e32 v150, v150
	v_exp_f32_e32 v151, v151
	v_exp_f32_e32 v152, v152
	v_exp_f32_e32 v153, v153
	v_exp_f32_e32 v154, v154
	v_exp_f32_e32 v155, v155
	v_fma_f32 v148, v148, v157, v157
	v_fma_f32 v149, v149, v157, v157
	v_fma_f32 v150, v150, v157, v157
	v_fma_f32 v151, v151, v157, v157
	v_fma_f32 v152, v152, v157, v157
	v_fma_f32 v153, v153, v157, v157
	v_fma_f32 v154, v154, v157, v157
	v_fma_f32 v155, v155, v157, v157
	v_rcp_f32_e32 v148, v148
	v_rcp_f32_e32 v149, v149
	v_rcp_f32_e32 v150, v150
	v_rcp_f32_e32 v151, v151
	v_rcp_f32_e32 v152, v152
	v_rcp_f32_e32 v153, v153
	v_rcp_f32_e32 v154, v154
	v_rcp_f32_e32 v155, v155
	v_mul_f32_e32 v28, v28, v24
	v_mul_f32_e32 v29, v29, v25
	v_mul_f32_e32 v30, v30, v26
	v_mul_f32_e32 v31, v31, v27
	v_mul_f32_e32 v20, v20, v16
	v_mul_f32_e32 v21, v21, v17
	v_mul_f32_e32 v22, v22, v18
	v_mul_f32_e32 v23, v23, v19
	v_mul_f32_e32 v28, v28, v148
	v_mul_f32_e32 v29, v29, v149
	v_mul_f32_e32 v30, v30, v150
	v_mul_f32_e32 v31, v31, v151
	v_mul_f32_e32 v20, v20, v152
	v_mul_f32_e32 v21, v21, v153
	v_mul_f32_e32 v22, v22, v154
	v_mul_f32_e32 v23, v23, v155
	v_cvt_pk_bf16_f32 v24, v28, v29
	v_cvt_pk_bf16_f32 v25, v30, v31
	v_cvt_pk_bf16_f32 v26, v20, v21
	v_cvt_pk_bf16_f32 v27, v22, v23
	global_store_dwordx4 v[164:165], v[24:27], off
	v_mul_f32_e32 v156, 0xbfb8aa3b, v251
	v_mul_f32_e32 v158, v251, v251
	v_rcp_f32_e32 v157, v158
	v_add_u32_e32 v166, 0xb0, v138
	v_mad_i64_i32 v[164:165], s[40:41], v166, s51, v[160:161]
	v_lshl_add_u64 v[164:165], v[164:165], 0, v[162:163]
	v_mul_f32_e32 v148, v12, v156
	v_mul_f32_e32 v149, v13, v156
	v_mul_f32_e32 v150, v14, v156
	v_mul_f32_e32 v151, v15, v156
	v_mul_f32_e32 v152, v4, v156
	v_mul_f32_e32 v153, v5, v156
	v_mul_f32_e32 v154, v6, v156
	v_mul_f32_e32 v155, v7, v156
	v_exp_f32_e32 v148, v148
	v_exp_f32_e32 v149, v149
	v_exp_f32_e32 v150, v150
	v_exp_f32_e32 v151, v151
	v_exp_f32_e32 v152, v152
	v_exp_f32_e32 v153, v153
	v_exp_f32_e32 v154, v154
	v_exp_f32_e32 v155, v155
	v_fma_f32 v148, v148, v157, v157
	v_fma_f32 v149, v149, v157, v157
	v_fma_f32 v150, v150, v157, v157
	v_fma_f32 v151, v151, v157, v157
	v_fma_f32 v152, v152, v157, v157
	v_fma_f32 v153, v153, v157, v157
	v_fma_f32 v154, v154, v157, v157
	v_fma_f32 v155, v155, v157, v157
	v_rcp_f32_e32 v148, v148
	v_rcp_f32_e32 v149, v149
	v_rcp_f32_e32 v150, v150
	v_rcp_f32_e32 v151, v151
	v_rcp_f32_e32 v152, v152
	v_rcp_f32_e32 v153, v153
	v_rcp_f32_e32 v154, v154
	v_rcp_f32_e32 v155, v155
	v_mul_f32_e32 v12, v12, v8
	v_mul_f32_e32 v13, v13, v9
	v_mul_f32_e32 v14, v14, v10
	v_mul_f32_e32 v15, v15, v11
	v_mul_f32_e32 v4, v4, v0
	v_mul_f32_e32 v5, v5, v1
	v_mul_f32_e32 v6, v6, v2
	v_mul_f32_e32 v7, v7, v3
	v_mul_f32_e32 v12, v12, v148
	v_mul_f32_e32 v13, v13, v149
	v_mul_f32_e32 v14, v14, v150
	v_mul_f32_e32 v15, v15, v151
	v_mul_f32_e32 v4, v4, v152
	v_mul_f32_e32 v5, v5, v153
	v_mul_f32_e32 v6, v6, v154
	v_mul_f32_e32 v7, v7, v155
	v_cvt_pk_bf16_f32 v8, v12, v13
	v_cvt_pk_bf16_f32 v9, v14, v15
	v_cvt_pk_bf16_f32 v10, v4, v5
	v_cvt_pk_bf16_f32 v11, v6, v7
	global_store_dwordx4 v[164:165], v[8:11], off
	s_mov_b64 s[58:59], -1
	s_andn2_b64 vcc, exec, s[38:39]
	s_cbranch_vccnz .LBB0_1698
	s_andn2_b64 vcc, exec, s[42:43]
	s_cbranch_vccnz .LBB0_1697
	s_barrier
	s_branch .LBB0_1697
